# hyena long-conv item rewritten: u blocks staged in LDS by LDS-DMA, fragments via ds_read_b128
# speedup vs baseline: 1.1318x; 1.0533x over previous
.LBB0_106:
	s_or_b64 exec, exec, s[0:1]
	s_waitcnt lgkmcnt(0)
	s_barrier
	s_waitcnt vmcnt(6)
	ds_read_b32 v0, v131 offset:43024
	s_movk_i32 s0, 0x77f
	v_readlane_b32 s2, v255, 31
	v_readlane_b32 s3, v255, 32
	s_waitcnt lgkmcnt(0)
	v_cmp_lt_i32_e32 vcc, s0, v0
	v_readfirstlane_b32 s25, v0
	s_mov_b64 s[0:1], -1
	s_cbranch_vccnz .LBB0_101
	s_cmpk_gt_i32 s25, 0x7f
	s_cbranch_scc0 .LBB0_139
	s_cmpk_gt_u32 s25, 0x47f
	s_cbranch_scc0 .LBB0_130
	s_cmpk_gt_u32 s25, 0x57f
	s_cbranch_scc0 .LBB0_125
	s_cmpk_gt_u32 s25, 0x5ff
	s_cbranch_scc0 .LBB0_120
	s_cmpk_gt_u32 s25, 0x6ff
	s_cbranch_scc0 .LBB0_115
	s_mov_b32 s26, 0
	s_add_i32 s27, s25, 0xfffff900
	s_branch .Lhy_common

.LBB0_120:
	s_andn2_b64 vcc, exec, s[0:1]
	s_cbranch_vccnz .LBB0_124
	s_mov_b32 s26, 1
	s_add_i32 s27, s25, 0xfffffa80
.Lhy_common:
	v_and_b32_e32 v167, 63, v128
	v_lshrrev_b32_e32 v168, 6, v128
	s_movk_i32 s28, 0x100
	v_readfirstlane_b32 s25, v168
	s_cmp_lg_u32 s26, 0
	s_cselect_b32 s28, 0x800, s28
	s_lshr_b32 s29, s28, 4
	s_lshl_b32 s90, s27, 2
	s_add_i32 s90, s90, s25
	v_readlane_b32 s0, v255, 44
	s_mul_i32 s0, s0, 0x920000
	s_mul_i32 s1, s26, 0x110000
	s_add_u32 s0, s0, s1
	s_add_u32 s4, s28, 16
	s_lshl_b32 s4, s4, 2
	s_mul_i32 s1, s90, s4
	s_lshl_b32 s1, s1, 1
	s_add_u32 s0, s0, s1
	s_add_u32 s0, s0, 0x5e24000
	s_add_u32 s36, s96, s0
	s_addc_u32 s37, s97, 0
	s_lshl_b32 s0, s90, 13
	s_lshl_b32 s1, s26, 12
	s_add_u32 s0, s0, s1
	s_lshl_b32 s1, s0, 1
	s_add_u32 s1, s1, 0x82a6100
	s_add_u32 s38, s96, s1
	s_addc_u32 s39, s97, 0
	s_lshl_b32 s1, s0, 2
	s_add_u32 s1, s1, 0x126a6100
	s_add_u32 s40, s96, s1
	s_addc_u32 s41, s97, 0
	v_lshlrev_b32_e32 v146, 4, v167
	s_lshl_b32 s0, s25, 13
	s_mov_b32 m0, s0
	v_add_u32_e32 v169, 0x1000, v146
	global_load_lds_dwordx4 v146, s[38:39] offset:0
	global_load_lds_dwordx4 v146, s[38:39] offset:1024
	global_load_lds_dwordx4 v146, s[38:39] offset:2048
	global_load_lds_dwordx4 v146, s[38:39] offset:3072
	s_add_u32 s1, s0, 0x1000
	s_mov_b32 m0, s1
	s_nop 0
	global_load_lds_dwordx4 v169, s[38:39] offset:0
	global_load_lds_dwordx4 v169, s[38:39] offset:1024
	global_load_lds_dwordx4 v169, s[38:39] offset:2048
	global_load_lds_dwordx4 v169, s[38:39] offset:3072
	v_and_b32_e32 v169, 15, v167
	v_lshlrev_b32_e32 v170, 9, v169
	v_add_u32_e32 v170, 0x8000, v170
	v_mov_b32_e32 v0, 0
	v_mov_b32_e32 v1, 0
	v_mov_b32_e32 v2, 0
	v_mov_b32_e32 v3, 0
	ds_write_b128 v170, v[0:3]
	v_mov_b32_e32 v143, 0x8000
	v_lshrrev_b32_e32 v168, 4, v167
	v_lshrrev_b32_e32 v170, 1, v168
	v_and_b32_e32 v168, 1, v168
	v_sub_u32_e32 v141, v169, v170
	v_add_u32_e32 v141, s29, v141
	v_lshlrev_b32_e32 v142, 5, v141
	v_lshl_add_u32 v142, v168, 4, v142
	v_add_u32_e32 v142, s0, v142
	s_lshl_b32 s1, s28, 1
	v_lshlrev_b32_e32 v170, 4, v170
	v_add_u32_e32 v170, v170, v169
	v_sub_u32_e32 v170, s1, v170
	v_lshl_add_u32 v170, v168, 3, v170
	v_lshrrev_b32_e32 v140, 1, v170
	v_lshlrev_b32_e32 v140, 2, v140
	v_and_b32_e32 v170, 1, v169
	v_mul_lo_u32 v170, v170, s4
	v_add_u32_e32 v140, v140, v170
	s_lshl_b32 s1, s26, 4
	s_mul_i32 s58, s1, 0
	s_mul_i32 s59, s1, 1
	s_mul_i32 s60, s1, 2
	s_mul_i32 s61, s1, 3
	s_mul_i32 s62, s1, 4
	s_mul_i32 s63, s1, 5
	s_mul_i32 s64, s1, 6
	s_mul_i32 s65, s1, 7
	v_lshrrev_b32_e32 v168, 4, v167
	v_lshlrev_b32_e32 v170, 6, v169
	v_lshl_add_u32 v163, v168, 4, v170
	v_add_u32_e32 v164, 0x1000, v163
	v_add_u32_e32 v165, 0x2000, v163
	v_add_u32_e32 v166, 0x3000, v163
	v_mov_b32_e32 v4, 0
	v_mov_b32_e32 v5, 0
	v_mov_b32_e32 v6, 0
	v_mov_b32_e32 v7, 0
	v_mov_b32_e32 v8, 0
	v_mov_b32_e32 v9, 0
	v_mov_b32_e32 v10, 0
	v_mov_b32_e32 v11, 0
	v_mov_b32_e32 v12, 0
	v_mov_b32_e32 v13, 0
	v_mov_b32_e32 v14, 0
	v_mov_b32_e32 v15, 0
	v_mov_b32_e32 v16, 0
	v_mov_b32_e32 v17, 0
	v_mov_b32_e32 v18, 0
	v_mov_b32_e32 v19, 0
	v_mov_b32_e32 v20, 0
	v_mov_b32_e32 v21, 0
	v_mov_b32_e32 v22, 0
	v_mov_b32_e32 v23, 0
	v_mov_b32_e32 v24, 0
	v_mov_b32_e32 v25, 0
	v_mov_b32_e32 v26, 0
	v_mov_b32_e32 v27, 0
	v_mov_b32_e32 v28, 0
	v_mov_b32_e32 v29, 0
	v_mov_b32_e32 v30, 0
	v_mov_b32_e32 v31, 0
	v_mov_b32_e32 v32, 0
	v_mov_b32_e32 v33, 0
	v_mov_b32_e32 v34, 0
	v_mov_b32_e32 v35, 0
	v_mov_b32_e32 v36, 0
	v_mov_b32_e32 v37, 0
	v_mov_b32_e32 v38, 0
	v_mov_b32_e32 v39, 0
	v_mov_b32_e32 v40, 0
	v_mov_b32_e32 v41, 0
	v_mov_b32_e32 v42, 0
	v_mov_b32_e32 v43, 0
	v_mov_b32_e32 v44, 0
	v_mov_b32_e32 v45, 0
	v_mov_b32_e32 v46, 0
	v_mov_b32_e32 v47, 0
	v_mov_b32_e32 v48, 0
	v_mov_b32_e32 v49, 0
	v_mov_b32_e32 v50, 0
	v_mov_b32_e32 v51, 0
	v_mov_b32_e32 v52, 0
	v_mov_b32_e32 v53, 0
	v_mov_b32_e32 v54, 0
	v_mov_b32_e32 v55, 0
	v_mov_b32_e32 v56, 0
	v_mov_b32_e32 v57, 0
	v_mov_b32_e32 v58, 0
	v_mov_b32_e32 v59, 0
	v_mov_b32_e32 v60, 0
	v_mov_b32_e32 v61, 0
	v_mov_b32_e32 v62, 0
	v_mov_b32_e32 v63, 0
	global_load_dwordx4 v[132:135], v140, s[36:37]
	v_add_u32_e32 v155, s58, v141
	v_add_u32_e32 v156, s59, v141
	v_add_u32_e32 v157, s60, v141
	v_add_u32_e32 v158, s61, v141
	v_add_u32_e32 v159, s62, v141
	v_add_u32_e32 v160, s63, v141
	v_add_u32_e32 v161, s64, v141
	v_add_u32_e32 v162, s65, v141
	v_cmp_gt_u32_e64 s[42:43], s29, v155
	v_cmp_gt_u32_e64 s[44:45], s29, v156
	v_cmp_gt_u32_e64 s[46:47], s29, v157
	v_cmp_gt_u32_e64 s[48:49], s29, v158
	v_cmp_gt_u32_e64 s[50:51], s29, v159
	v_cmp_gt_u32_e64 s[52:53], s29, v160
	v_cmp_gt_u32_e64 s[54:55], s29, v161
	v_cmp_gt_u32_e64 s[56:57], s29, v162
	v_cndmask_b32_e64 v147, v143, v142, s[42:43]
	v_cndmask_b32_e64 v148, v143, v142, s[44:45]
	v_cndmask_b32_e64 v149, v143, v142, s[46:47]
	v_cndmask_b32_e64 v150, v143, v142, s[48:49]
	v_cndmask_b32_e64 v151, v143, v142, s[50:51]
	v_cndmask_b32_e64 v152, v143, v142, s[52:53]
	v_cndmask_b32_e64 v153, v143, v142, s[54:55]
	v_cndmask_b32_e64 v154, v143, v142, s[56:57]
	s_lshr_b32 s88, s29, 1
	s_waitcnt vmcnt(1)
	s_waitcnt lgkmcnt(0)
.Lhy_loop:
	ds_read_b128 v[64:67], v147 offset:0
	ds_read_b128 v[68:71], v148 offset:512
	ds_read_b128 v[72:75], v149 offset:1024
	ds_read_b128 v[76:79], v150 offset:1536
	ds_read_b128 v[80:83], v151 offset:2048
	ds_read_b128 v[84:87], v152 offset:2560
	ds_read_b128 v[88:91], v153 offset:3072
	ds_read_b128 v[92:95], v154 offset:3584
	ds_read_b128 v[96:99], v147 offset:4096
	ds_read_b128 v[100:103], v148 offset:4608
	ds_read_b128 v[104:107], v149 offset:5120
	ds_read_b128 v[108:111], v150 offset:5632
	ds_read_b128 v[112:115], v151 offset:6144
	ds_read_b128 v[116:119], v152 offset:6656
	ds_read_b128 v[120:123], v153 offset:7168
	ds_read_b128 v[124:127], v154 offset:7680
	v_add_u32_e32 v140, -64, v140
	v_max_i32_e32 v167, 0, v140
	global_load_dwordx4 v[136:139], v167, s[36:37]
	v_add_u32_e32 v141, -2, v141
	v_add_u32_e32 v142, -64, v142
	v_add_u32_e32 v155, s58, v141
	v_add_u32_e32 v156, s59, v141
	v_add_u32_e32 v157, s60, v141
	v_add_u32_e32 v158, s61, v141
	v_add_u32_e32 v159, s62, v141
	v_add_u32_e32 v160, s63, v141
	v_add_u32_e32 v161, s64, v141
	v_add_u32_e32 v162, s65, v141
	v_cmp_gt_u32_e64 s[42:43], s29, v155
	v_cmp_gt_u32_e64 s[44:45], s29, v156
	v_cmp_gt_u32_e64 s[46:47], s29, v157
	v_cmp_gt_u32_e64 s[48:49], s29, v158
	v_cmp_gt_u32_e64 s[50:51], s29, v159
	v_cmp_gt_u32_e64 s[52:53], s29, v160
	v_cmp_gt_u32_e64 s[54:55], s29, v161
	v_cmp_gt_u32_e64 s[56:57], s29, v162
	v_cndmask_b32_e64 v147, v143, v142, s[42:43]
	v_cndmask_b32_e64 v148, v143, v142, s[44:45]
	v_cndmask_b32_e64 v149, v143, v142, s[46:47]
	v_cndmask_b32_e64 v150, v143, v142, s[48:49]
	v_cndmask_b32_e64 v151, v143, v142, s[50:51]
	v_cndmask_b32_e64 v152, v143, v142, s[52:53]
	v_cndmask_b32_e64 v153, v143, v142, s[54:55]
	v_cndmask_b32_e64 v154, v143, v142, s[56:57]
	s_waitcnt vmcnt(1)
	s_waitcnt lgkmcnt(15)
	v_mfma_f32_16x16x32_bf16 v[0:3], v[132:135], v[64:67], v[0:3]
	s_waitcnt lgkmcnt(14)
	v_mfma_f32_16x16x32_bf16 v[4:7], v[132:135], v[68:71], v[4:7]
	s_waitcnt lgkmcnt(13)
	v_mfma_f32_16x16x32_bf16 v[8:11], v[132:135], v[72:75], v[8:11]
	s_waitcnt lgkmcnt(12)
	v_mfma_f32_16x16x32_bf16 v[12:15], v[132:135], v[76:79], v[12:15]
	s_waitcnt lgkmcnt(11)
	v_mfma_f32_16x16x32_bf16 v[16:19], v[132:135], v[80:83], v[16:19]
	s_waitcnt lgkmcnt(10)
	v_mfma_f32_16x16x32_bf16 v[20:23], v[132:135], v[84:87], v[20:23]
	s_waitcnt lgkmcnt(9)
	v_mfma_f32_16x16x32_bf16 v[24:27], v[132:135], v[88:91], v[24:27]
	s_waitcnt lgkmcnt(8)
	v_mfma_f32_16x16x32_bf16 v[28:31], v[132:135], v[92:95], v[28:31]
	s_waitcnt lgkmcnt(7)
	v_mfma_f32_16x16x32_bf16 v[32:35], v[132:135], v[96:99], v[32:35]
	s_waitcnt lgkmcnt(6)
	v_mfma_f32_16x16x32_bf16 v[36:39], v[132:135], v[100:103], v[36:39]
	s_waitcnt lgkmcnt(5)
	v_mfma_f32_16x16x32_bf16 v[40:43], v[132:135], v[104:107], v[40:43]
	s_waitcnt lgkmcnt(4)
	v_mfma_f32_16x16x32_bf16 v[44:47], v[132:135], v[108:111], v[44:47]
	s_waitcnt lgkmcnt(3)
	v_mfma_f32_16x16x32_bf16 v[48:51], v[132:135], v[112:115], v[48:51]
	s_waitcnt lgkmcnt(2)
	v_mfma_f32_16x16x32_bf16 v[52:55], v[132:135], v[116:119], v[52:55]
	s_waitcnt lgkmcnt(1)
	v_mfma_f32_16x16x32_bf16 v[56:59], v[132:135], v[120:123], v[56:59]
	s_waitcnt lgkmcnt(0)
	v_mfma_f32_16x16x32_bf16 v[60:63], v[132:135], v[124:127], v[60:63]
	ds_read_b128 v[64:67], v147 offset:0
	ds_read_b128 v[68:71], v148 offset:512
	ds_read_b128 v[72:75], v149 offset:1024
	ds_read_b128 v[76:79], v150 offset:1536
	ds_read_b128 v[80:83], v151 offset:2048
	ds_read_b128 v[84:87], v152 offset:2560
	ds_read_b128 v[88:91], v153 offset:3072
	ds_read_b128 v[92:95], v154 offset:3584
	ds_read_b128 v[96:99], v147 offset:4096
	ds_read_b128 v[100:103], v148 offset:4608
	ds_read_b128 v[104:107], v149 offset:5120
	ds_read_b128 v[108:111], v150 offset:5632
	ds_read_b128 v[112:115], v151 offset:6144
	ds_read_b128 v[116:119], v152 offset:6656
	ds_read_b128 v[120:123], v153 offset:7168
	ds_read_b128 v[124:127], v154 offset:7680
	v_add_u32_e32 v140, -64, v140
	v_max_i32_e32 v167, 0, v140
	global_load_dwordx4 v[132:135], v167, s[36:37]
	v_add_u32_e32 v141, -2, v141
	v_add_u32_e32 v142, -64, v142
	v_add_u32_e32 v155, s58, v141
	v_add_u32_e32 v156, s59, v141
	v_add_u32_e32 v157, s60, v141
	v_add_u32_e32 v158, s61, v141
	v_add_u32_e32 v159, s62, v141
	v_add_u32_e32 v160, s63, v141
	v_add_u32_e32 v161, s64, v141
	v_add_u32_e32 v162, s65, v141
	v_cmp_gt_u32_e64 s[42:43], s29, v155
	v_cmp_gt_u32_e64 s[44:45], s29, v156
	v_cmp_gt_u32_e64 s[46:47], s29, v157
	v_cmp_gt_u32_e64 s[48:49], s29, v158
	v_cmp_gt_u32_e64 s[50:51], s29, v159
	v_cmp_gt_u32_e64 s[52:53], s29, v160
	v_cmp_gt_u32_e64 s[54:55], s29, v161
	v_cmp_gt_u32_e64 s[56:57], s29, v162
	v_cndmask_b32_e64 v147, v143, v142, s[42:43]
	v_cndmask_b32_e64 v148, v143, v142, s[44:45]
	v_cndmask_b32_e64 v149, v143, v142, s[46:47]
	v_cndmask_b32_e64 v150, v143, v142, s[48:49]
	v_cndmask_b32_e64 v151, v143, v142, s[50:51]
	v_cndmask_b32_e64 v152, v143, v142, s[52:53]
	v_cndmask_b32_e64 v153, v143, v142, s[54:55]
	v_cndmask_b32_e64 v154, v143, v142, s[56:57]
	s_waitcnt vmcnt(1)
	s_waitcnt lgkmcnt(15)
	v_mfma_f32_16x16x32_bf16 v[0:3], v[136:139], v[64:67], v[0:3]
	s_waitcnt lgkmcnt(14)
	v_mfma_f32_16x16x32_bf16 v[4:7], v[136:139], v[68:71], v[4:7]
	s_waitcnt lgkmcnt(13)
	v_mfma_f32_16x16x32_bf16 v[8:11], v[136:139], v[72:75], v[8:11]
	s_waitcnt lgkmcnt(12)
	v_mfma_f32_16x16x32_bf16 v[12:15], v[136:139], v[76:79], v[12:15]
	s_waitcnt lgkmcnt(11)
	v_mfma_f32_16x16x32_bf16 v[16:19], v[136:139], v[80:83], v[16:19]
	s_waitcnt lgkmcnt(10)
	v_mfma_f32_16x16x32_bf16 v[20:23], v[136:139], v[84:87], v[20:23]
	s_waitcnt lgkmcnt(9)
	v_mfma_f32_16x16x32_bf16 v[24:27], v[136:139], v[88:91], v[24:27]
	s_waitcnt lgkmcnt(8)
	v_mfma_f32_16x16x32_bf16 v[28:31], v[136:139], v[92:95], v[28:31]
	s_waitcnt lgkmcnt(7)
	v_mfma_f32_16x16x32_bf16 v[32:35], v[136:139], v[96:99], v[32:35]
	s_waitcnt lgkmcnt(6)
	v_mfma_f32_16x16x32_bf16 v[36:39], v[136:139], v[100:103], v[36:39]
	s_waitcnt lgkmcnt(5)
	v_mfma_f32_16x16x32_bf16 v[40:43], v[136:139], v[104:107], v[40:43]
	s_waitcnt lgkmcnt(4)
	v_mfma_f32_16x16x32_bf16 v[44:47], v[136:139], v[108:111], v[44:47]
	s_waitcnt lgkmcnt(3)
	v_mfma_f32_16x16x32_bf16 v[48:51], v[136:139], v[112:115], v[48:51]
	s_waitcnt lgkmcnt(2)
	v_mfma_f32_16x16x32_bf16 v[52:55], v[136:139], v[116:119], v[52:55]
	s_waitcnt lgkmcnt(1)
	v_mfma_f32_16x16x32_bf16 v[56:59], v[136:139], v[120:123], v[56:59]
	s_waitcnt lgkmcnt(0)
	v_mfma_f32_16x16x32_bf16 v[60:63], v[136:139], v[124:127], v[60:63]
	s_add_i32 s88, s88, -1
	s_cmp_lg_u32 s88, 0
	s_cbranch_scc1 .Lhy_loop
	s_nop 7
	global_store_dwordx4 v163, v[0:3], s[40:41] offset:0
	global_store_dwordx4 v163, v[4:7], s[40:41] offset:1024
	global_store_dwordx4 v163, v[8:11], s[40:41] offset:2048
	global_store_dwordx4 v163, v[12:15], s[40:41] offset:3072
	global_store_dwordx4 v164, v[16:19], s[40:41] offset:0
	global_store_dwordx4 v164, v[20:23], s[40:41] offset:1024
	global_store_dwordx4 v164, v[24:27], s[40:41] offset:2048
	global_store_dwordx4 v164, v[28:31], s[40:41] offset:3072
	global_store_dwordx4 v165, v[32:35], s[40:41] offset:0
	global_store_dwordx4 v165, v[36:39], s[40:41] offset:1024
	global_store_dwordx4 v165, v[40:43], s[40:41] offset:2048
	global_store_dwordx4 v165, v[44:47], s[40:41] offset:3072
	global_store_dwordx4 v166, v[48:51], s[40:41] offset:0
	global_store_dwordx4 v166, v[52:55], s[40:41] offset:1024
	global_store_dwordx4 v166, v[56:59], s[40:41] offset:2048
	global_store_dwordx4 v166, v[60:63], s[40:41] offset:3072
	s_waitcnt vmcnt(16)
	s_branch .LBB0_100
